# merge GEMM: drop the per-unit vmcnt(0) drain, let the first two K-loop waits of a following unit leave the 16 epilogue stores in flight (vmcnt 24)
# speedup vs baseline: 1.0016x; 1.0016x over previous
; #define PG8_STAGE(bufoff, gbase, voff) do { _Pragma("unroll") for (int _i = 0; _i < 2; ++_i) \
;         __builtin_amdgcn_global_load_lds((const unsigned*)((const char*)(gbase) + (voff)[_i]), (PG8_LAS unsigned*)(lds + (bufoff) + ldsw + _i * 8192), 16, 0, 0); } while (0)
; #define PG8_WAIT_V(n) asm volatile("s_waitcnt vmcnt(" #n ")" ::: "memory")
; #define PG8_BAR __builtin_amdgcn_s_barrier()
; template <class Epi, class Sched, bool ALIGN_EPI = false, bool SP2 = false>
; __device__ __forceinline__ void gemm_phase(PG8_LAS unsigned char* lds, const Gemm g, const Sched& S, const Epi& E) {
;     ...
;         PG8_STAGE(PG8_SB(1, 0), cB + kstep, voffB); PG8_STAGE(PG8_SA(1, 0), cA + kstep, voffA); PG8_STAGE(PG8_SB(1, 1), cB + hstep + kstep, voffB);
;         PG8_WAIT_V(6); PG8_BAR;
;     ...
;     for (;;) {
;         const bool has_next = S.next(ui + 1, nxt);
;         const char* nA = has_next ? (const char*)g.A + (size_t)nxt.pm * tstep : cA; const char* nB = has_next ? (const char*)g.Bt + (size_t)nxt.pn * tstep : cB;
;         for (int t = 0; t < nt; t += 2) {
.LBB0_1296:
	s_mov_b64 s[12:13], 0x80
	s_add_i32 m0, s35, 0x18000
	v_lshl_add_u64 v[10:11], v[10:11], 0, s[12:13]
	s_waitcnt vmcnt(2)
	s_barrier
	global_load_lds_dwordx4 v[10:11], off
	v_lshl_add_u64 v[6:7], v[6:7], 0, s[12:13]
	s_add_i32 m0, s35, 0x1a000
	s_add_i32 s40, s35, 0x8000
	global_load_lds_dwordx4 v[6:7], off
	v_lshl_add_u64 v[6:7], v[8:9], 0, s[12:13]
	s_mov_b32 m0, s40
	s_add_i32 s41, s35, 0xa000
	global_load_lds_dwordx4 v[6:7], off
	v_lshl_add_u64 v[6:7], v[12:13], 0, s[12:13]
	s_mov_b32 m0, s41
	v_lshl_add_u64 v[4:5], v[4:5], 0, s[12:13]
	global_load_lds_dwordx4 v[6:7], off
	s_add_i32 m0, s35, 0x1c000
	v_lshl_add_u64 v[2:3], v[2:3], 0, s[12:13]
	global_load_lds_dwordx4 v[4:5], off
	s_add_i32 m0, s35, 0x1e000
	v_bfe_u32 v199, v200, 4, 2
	global_load_lds_dwordx4 v[2:3], off
	s_lshr_b32 s1, s1, 26
	v_and_b32_e32 v198, 15, v200
	s_add_i32 s1, s0, s1
	v_lshlrev_b32_e32 v2, 4, v199
	v_lshlrev_b32_e32 v4, 2, v200
	s_ashr_i32 s42, s1, 6
	v_lshl_or_b32 v3, v198, 6, v2
	s_lshl_b32 s1, s3, 13
	v_and_b32_e32 v4, 32, v4
	v_bitop3_b32 v5, v3, s1, v4 bitop3:0xde
	s_lshl_b32 s1, s14, 5
	s_sext_i32_i8 s57, s2
	s_and_b32 s1, s1, 0x60
	v_lshlrev_b32_e32 v3, 6, v200
	s_movk_i32 s2, 0x3c0
	s_lshl_b32 s43, s3, 6
	v_and_or_b32 v2, v3, s2, v2
	s_lshl_b32 s2, s1, 7
	v_bitop3_b32 v201, s2, v2, v4 bitop3:0xf6
	s_cmp_gt_i32 s0, 63
	v_add_u32_e32 v2, v16, v15
	s_cselect_b64 s[14:15], -1, 0
	s_lshl_b32 s1, s1, 1
	v_mul_lo_u32 v2, s0, v2
	s_add_u32 s44, s88, s1
	v_lshlrev_b32_e32 v2, 1, v2
	s_addc_u32 s45, s89, 0
	s_add_i32 s46, s42, -2
	v_add3_u32 v2, v1, v2, v14
	v_mov_b32_e32 v3, v0
	s_cmpk_lt_u32 s16, 0x100
	v_lshl_add_u64 v[2:3], s[6:7], 0, v[2:3]
	s_cselect_b64 s[16:17], -1, 0
	s_add_u32 s47, s44, 0x4000000
	v_lshl_add_u64 v[180:181], v[2:3], 0, s[12:13]
	v_add_u32_e32 v2, v17, v15
	s_addc_u32 s48, s45, 0
	v_mul_lo_u32 v2, s0, v2
	s_add_u32 s1, s90, s1
	v_lshlrev_b32_e32 v2, 1, v2
	s_waitcnt vmcnt(6)
	s_addc_u32 s2, s91, 0
	v_add3_u32 v2, v1, v2, v14
	v_mov_b32_e32 v3, v0
	s_add_u32 s49, s1, 0x5000000
	v_lshl_add_u64 v[2:3], s[6:7], 0, v[2:3]
	s_addc_u32 s50, s2, 0
	s_ashr_i32 s51, s83, 31
	v_lshl_add_u64 v[182:183], v[2:3], 0, s[12:13]
	v_mov_b64_e32 v[184:185], 0x200
	v_mov_b64_e32 v[186:187], 0x1ff
	s_add_i32 s52, 0, 0x10000
	s_add_i32 s53, 0, 0x14000
	v_add_u32_e32 v202, 0, v5
	s_barrier
	s_mov_b32 s99, 0
	s_branch .LBB0_1299

; template <class Epi, class Sched, bool ALIGN_EPI = false, bool SP2 = false>
; __device__ __forceinline__ void gemm_phase(PG8_LAS unsigned char* lds, const Gemm g, const Sched& S, const Epi& E) {
;     ...
;             if constexpr (Epi::HAS_MID) { if (t == Epi::MID_T) E.mid(acc, cur, wr, wc, fr, fq); }
;     ...
;         if (!has_next) break;
; #pragma unroll
;         for (int a = 0; a < 2; ++a)
; #pragma unroll
;             for (int b = 0; b < 2; ++b)
; #pragma unroll
;                 for (int m = 0; m < 4; ++m)
; #pragma unroll
;                     for (int n = 0; n < 2; ++n) acc[a][b][m][n] = (f32x4){0.f, 0.f, 0.f, 0.f};
;         cur = nxt; cA = nA; cB = nB; ++ui;
.LBB0_1309:
	s_andn2_b64 vcc, exec, s[14:15]
	s_cbranch_vccnz .LBB0_1314
	s_lshl_b32 s22, s57, 8
	s_lshl_b32 s58, s56, 8
	s_ashr_i32 s23, s22, 31
	s_add_i32 s58, s58, s43
	s_lshl_b64 s[22:23], s[22:23], 1
	s_add_u32 s22, s44, s22
	s_addc_u32 s23, s45, s23
	v_mov_b32_e32 v2, v0
	v_mov_b32_e32 v3, v0
	s_add_u32 s59, s24, 0x100
	v_mov_b32_e32 v1, v0
	v_mov_b64_e32 v[6:7], v[2:3]
	v_mov_b64_e32 v[10:11], v[2:3]
	v_mov_b64_e32 v[22:23], v[2:3]
	v_mov_b64_e32 v[26:27], v[2:3]
	v_mov_b64_e32 v[38:39], v[2:3]
	v_mov_b64_e32 v[42:43], v[2:3]
	v_mov_b64_e32 v[54:55], v[2:3]
	v_mov_b64_e32 v[58:59], v[2:3]
	v_mov_b64_e32 v[14:15], v[2:3]
	v_mov_b64_e32 v[18:19], v[2:3]
	v_mov_b64_e32 v[30:31], v[2:3]
	v_mov_b64_e32 v[34:35], v[2:3]
	v_mov_b64_e32 v[46:47], v[2:3]
	v_mov_b64_e32 v[50:51], v[2:3]
	v_mov_b64_e32 v[62:63], v[2:3]
	v_mov_b64_e32 v[66:67], v[2:3]
	v_mov_b64_e32 v[70:71], v[2:3]
	v_mov_b64_e32 v[74:75], v[2:3]
	v_mov_b64_e32 v[86:87], v[2:3]
	v_mov_b64_e32 v[90:91], v[2:3]
	v_mov_b64_e32 v[102:103], v[2:3]
	v_mov_b64_e32 v[106:107], v[2:3]
	v_mov_b64_e32 v[126:127], v[2:3]
	v_mov_b64_e32 v[130:131], v[2:3]
	v_mov_b64_e32 v[78:79], v[2:3]
	v_mov_b64_e32 v[82:83], v[2:3]
	v_mov_b64_e32 v[94:95], v[2:3]
	v_mov_b64_e32 v[98:99], v[2:3]
	v_mov_b64_e32 v[110:111], v[2:3]
	v_mov_b64_e32 v[114:115], v[2:3]
	v_mov_b64_e32 v[122:123], v[2:3]
	v_mov_b64_e32 v[118:119], v[2:3]
	s_addc_u32 s60, s25, 0
	v_lshl_add_u64 v[168:169], s[20:21], 0, v[180:181]
	v_lshl_add_u64 v[170:171], s[20:21], 0, v[182:183]
	s_mov_b32 s26, 0
	s_mov_b64 s[24:25], 0
	v_mov_b64_e32 v[4:5], v[0:1]
	v_mov_b64_e32 v[8:9], v[0:1]
	v_mov_b64_e32 v[20:21], v[0:1]
	v_mov_b64_e32 v[24:25], v[0:1]
	v_mov_b64_e32 v[36:37], v[0:1]
	v_mov_b64_e32 v[40:41], v[0:1]
	v_mov_b64_e32 v[52:53], v[0:1]
	v_mov_b64_e32 v[56:57], v[0:1]
	v_mov_b64_e32 v[12:13], v[0:1]
	v_mov_b64_e32 v[16:17], v[0:1]
	v_mov_b64_e32 v[28:29], v[0:1]
	v_mov_b64_e32 v[32:33], v[0:1]
	v_mov_b64_e32 v[44:45], v[0:1]
	v_mov_b64_e32 v[48:49], v[0:1]
	v_mov_b64_e32 v[60:61], v[0:1]
	v_mov_b64_e32 v[64:65], v[0:1]
	v_mov_b64_e32 v[68:69], v[0:1]
	v_mov_b64_e32 v[72:73], v[0:1]
	v_mov_b64_e32 v[84:85], v[0:1]
	v_mov_b64_e32 v[88:89], v[0:1]
	v_mov_b64_e32 v[100:101], v[0:1]
	v_mov_b64_e32 v[104:105], v[0:1]
	v_mov_b64_e32 v[124:125], v[0:1]
	v_mov_b64_e32 v[128:129], v[0:1]
	v_mov_b64_e32 v[76:77], v[0:1]
	v_mov_b64_e32 v[80:81], v[0:1]
	v_mov_b64_e32 v[92:93], v[0:1]
	v_mov_b64_e32 v[96:97], v[0:1]
	v_mov_b64_e32 v[108:109], v[0:1]
	v_mov_b64_e32 v[112:113], v[0:1]
	v_mov_b64_e32 v[120:121], v[0:1]
	v_mov_b64_e32 v[116:117], v[0:1]
	s_cmp_lg_u32 s26, 16
	s_cbranch_scc1 .LBB0_1312

; #define PG8_STAGE(bufoff, gbase, voff) do { _Pragma("unroll") for (int _i = 0; _i < 2; ++_i) \
;         __builtin_amdgcn_global_load_lds((const unsigned*)((const char*)(gbase) + (voff)[_i]), (PG8_LAS unsigned*)(lds + (bufoff) + ldsw + _i * 8192), 16, 0, 0); } while (0)
; #define PG8_LDA(dst, b, h) do { _Pragma("unroll") for (int m = 0; m < 4; ++m) _Pragma("unroll") for (int k = 0; k < 2; ++k) dst[m][k] = *(const PG8_LAS bf16x8*)(lds + PG8_SA(b, h) + aoff + m * 2048 + k * 1024); } while (0)
; #define PG8_LDB(dst, b, h) do { _Pragma("unroll") for (int n = 0; n < 2; ++n) _Pragma("unroll") for (int k = 0; k < 2; ++k) dst[n][k] = *(const PG8_LAS bf16x8*)(lds + PG8_SB(b, h) + boff + n * 2048 + k * 1024); } while (0)
; #define PG8_MMA(ai, bj, At, Bt) do { __builtin_amdgcn_s_setprio(1); _Pragma("unroll") for (int m = 0; m < 4; ++m) _Pragma("unroll") for (int n = 0; n < 2; ++n) _Pragma("unroll") for (int k = 0; k < 2; ++k) \
;         acc[ai][bj][m][n] = __builtin_amdgcn_mfma_f32_16x16x32_bf16(Bt[n][k], At[m][k], acc[ai][bj][m][n], 0, 0, 0); __builtin_amdgcn_s_setprio(0); } while (0)
; #define PG8_WAIT_V(n) asm volatile("s_waitcnt vmcnt(" #n ")" ::: "memory")
; #define PG8_WAIT_L(n) asm volatile("s_waitcnt lgkmcnt(" #n ")" ::: "memory")
; #define PG8_BAR __builtin_amdgcn_s_barrier()
; #define PG8_SCHED __builtin_amdgcn_sched_barrier(0)
; template <class Epi, class Sched, bool ALIGN_EPI = false, bool SP2 = false>
; __device__ __forceinline__ void gemm_phase(PG8_LAS unsigned char* lds, const Gemm g, const Sched& S, const Epi& E) {
;     ...
;             PG8_LDB(B0, 0, 0); PG8_LDB(B1, 0, 1); PG8_SCHED; PG8_LDA(At, 0, 0); PG8_STAGE(PG8_SA(1, 1), a1 + hstep, voffA);
;             PG8_WAIT_V(8); PG8_WAIT_L(0); PG8_BAR; PG8_MMA(0, 0, At, B0); PG8_MMA(0, 1, At, B1); PG8_BAR; PG8_SCHED;
.LBB0_1312:
	v_add_u32_e32 v1, s52, v201
	s_add_i32 s61, s26, 2
	ds_read_b128 v[132:135], v1
	ds_read_b128 v[136:139], v1 offset:1024
	ds_read_b128 v[140:143], v1 offset:2048
	ds_read_b128 v[144:147], v1 offset:3072
	v_add_u32_e32 v1, s53, v201
	s_add_u32 s27, s20, s24
	ds_read_b128 v[148:151], v1
	ds_read_b128 v[152:155], v1 offset:1024
	ds_read_b128 v[156:159], v1 offset:2048
	ds_read_b128 v[160:163], v1 offset:3072
	s_addc_u32 s62, s21, s25
	s_add_u32 s63, s27, 0x100
	s_addc_u32 s27, s62, 0
	s_add_u32 s62, s59, s24
	s_addc_u32 s64, s60, s25
	s_cmp_eq_u32 s46, s26
	s_cselect_b32 s27, s1, s27
	s_cselect_b32 s26, s0, s63
	s_cselect_b32 s63, s19, s64
	s_cselect_b32 s62, s18, s62
	v_lshl_add_u64 v[2:3], v[168:169], 0, s[24:25]
	s_add_i32 m0, s35, 0xc000
	ds_read_b128 v[164:167], v202
	ds_read_b128 v[188:191], v202 offset:1024
	ds_read_b128 v[192:195], v202 offset:2048
	ds_read_b128 v[204:207], v202 offset:3072
	ds_read_b128 v[208:211], v202 offset:4096
	ds_read_b128 v[212:215], v202 offset:5120
	ds_read_b128 v[216:219], v202 offset:6144
	ds_read_b128 v[220:223], v202 offset:7168
	global_load_lds_dwordx4 v[2:3], off
	v_lshl_add_u64 v[2:3], v[170:171], 0, s[24:25]
	s_add_i32 m0, s35, 0xe000
	s_nop 0
	global_load_lds_dwordx4 v[2:3], off
	s_cmp_eq_u32 s99, 0
	s_cbranch_scc1 .Lmw8_1
	s_waitcnt vmcnt(24)
	s_branch .Lmwj_1

; #define PG8_STAGE(bufoff, gbase, voff) do { _Pragma("unroll") for (int _i = 0; _i < 2; ++_i) \
;         __builtin_amdgcn_global_load_lds((const unsigned*)((const char*)(gbase) + (voff)[_i]), (PG8_LAS unsigned*)(lds + (bufoff) + ldsw + _i * 8192), 16, 0, 0); } while (0)
; #define PG8_LDA(dst, b, h) do { _Pragma("unroll") for (int m = 0; m < 4; ++m) _Pragma("unroll") for (int k = 0; k < 2; ++k) dst[m][k] = *(const PG8_LAS bf16x8*)(lds + PG8_SA(b, h) + aoff + m * 2048 + k * 1024); } while (0)
; #define PG8_MMA(ai, bj, At, Bt) do { __builtin_amdgcn_s_setprio(1); _Pragma("unroll") for (int m = 0; m < 4; ++m) _Pragma("unroll") for (int n = 0; n < 2; ++n) _Pragma("unroll") for (int k = 0; k < 2; ++k) \
;         acc[ai][bj][m][n] = __builtin_amdgcn_mfma_f32_16x16x32_bf16(Bt[n][k], At[m][k], acc[ai][bj][m][n], 0, 0, 0); __builtin_amdgcn_s_setprio(0); } while (0)
; #define PG8_WAIT_V(n) asm volatile("s_waitcnt vmcnt(" #n ")" ::: "memory")
; #define PG8_WAIT_L(n) asm volatile("s_waitcnt lgkmcnt(" #n ")" ::: "memory")
; #define PG8_BAR __builtin_amdgcn_s_barrier()
; #define PG8_SCHED __builtin_amdgcn_sched_barrier(0)
; template <class Epi, class Sched, bool ALIGN_EPI = false, bool SP2 = false>
; __device__ __forceinline__ void gemm_phase(PG8_LAS unsigned char* lds, const Gemm g, const Sched& S, const Epi& E) {
;     ...
;             PG8_WAIT_V(8); PG8_WAIT_L(0); PG8_BAR; PG8_MMA(0, 0, At, B0); PG8_MMA(0, 1, At, B1); PG8_BAR; PG8_SCHED;
;             PG8_LDA(At, 0, 1); PG8_STAGE(PG8_SB(0, 0), b2, voffB); PG8_STAGE(PG8_SB(0, 1), b2 + hstep, voffB); PG8_STAGE(PG8_SA(0, 0), a2, voffA);
.Lmwj_1:
	s_waitcnt lgkmcnt(0)
	s_barrier
	s_setprio 1
	s_waitcnt lgkmcnt(0)
	v_mfma_f32_16x16x32_bf16 v[116:119], v[132:135], v[164:167], v[116:119]
	v_mfma_f32_16x16x32_bf16 v[120:123], v[140:143], v[164:167], v[120:123]
	v_mfma_f32_16x16x32_bf16 v[112:115], v[132:135], v[192:195], v[112:115]
	v_mfma_f32_16x16x32_bf16 v[108:111], v[140:143], v[192:195], v[108:111]
	v_mfma_f32_16x16x32_bf16 v[96:99], v[132:135], v[208:211], v[96:99]
	v_mfma_f32_16x16x32_bf16 v[92:95], v[140:143], v[208:211], v[92:95]
	v_mfma_f32_16x16x32_bf16 v[80:83], v[132:135], v[216:219], v[80:83]
	v_mfma_f32_16x16x32_bf16 v[76:79], v[140:143], v[216:219], v[76:79]
	v_mfma_f32_16x16x32_bf16 v[116:119], v[136:139], v[188:191], v[116:119]
	v_mfma_f32_16x16x32_bf16 v[120:123], v[144:147], v[188:191], v[120:123]
	v_mfma_f32_16x16x32_bf16 v[112:115], v[136:139], v[204:207], v[112:115]
	v_mfma_f32_16x16x32_bf16 v[108:111], v[144:147], v[204:207], v[108:111]
	v_mfma_f32_16x16x32_bf16 v[96:99], v[136:139], v[212:215], v[96:99]
	v_mfma_f32_16x16x32_bf16 v[92:95], v[144:147], v[212:215], v[92:95]
	v_mfma_f32_16x16x32_bf16 v[80:83], v[136:139], v[220:223], v[80:83]
	v_mfma_f32_16x16x32_bf16 v[76:79], v[144:147], v[220:223], v[76:79]
	s_setprio 0
	s_setprio 1
	v_mfma_f32_16x16x32_bf16 v[128:131], v[148:151], v[164:167], v[128:131]
	v_mfma_f32_16x16x32_bf16 v[124:127], v[156:159], v[164:167], v[124:127]
	v_mfma_f32_16x16x32_bf16 v[104:107], v[148:151], v[192:195], v[104:107]
	v_mfma_f32_16x16x32_bf16 v[100:103], v[156:159], v[192:195], v[100:103]
	v_mfma_f32_16x16x32_bf16 v[88:91], v[148:151], v[208:211], v[88:91]
	v_mfma_f32_16x16x32_bf16 v[84:87], v[156:159], v[208:211], v[84:87]
	v_mfma_f32_16x16x32_bf16 v[72:75], v[148:151], v[216:219], v[72:75]
	v_mfma_f32_16x16x32_bf16 v[68:71], v[156:159], v[216:219], v[68:71]
	v_mfma_f32_16x16x32_bf16 v[128:131], v[152:155], v[188:191], v[128:131]
	v_mfma_f32_16x16x32_bf16 v[124:127], v[160:163], v[188:191], v[124:127]
	v_mfma_f32_16x16x32_bf16 v[104:107], v[152:155], v[204:207], v[104:107]
	v_mfma_f32_16x16x32_bf16 v[100:103], v[160:163], v[204:207], v[100:103]
	v_mfma_f32_16x16x32_bf16 v[88:91], v[152:155], v[212:215], v[88:91]
	v_mfma_f32_16x16x32_bf16 v[84:87], v[160:163], v[212:215], v[84:87]
	v_mfma_f32_16x16x32_bf16 v[72:75], v[152:155], v[220:223], v[72:75]
	v_mfma_f32_16x16x32_bf16 v[68:71], v[160:163], v[220:223], v[68:71]
	s_setprio 0
	s_barrier
	s_add_i32 s64, s52, s34
	v_lshl_add_u64 v[196:197], s[62:63], 0, v[174:175]
	s_mov_b32 m0, s64
	ds_read_b128 v[164:167], v202 offset:16384
	ds_read_b128 v[188:191], v202 offset:17408
	ds_read_b128 v[192:195], v202 offset:18432
	ds_read_b128 v[204:207], v202 offset:19456
	ds_read_b128 v[208:211], v202 offset:20480
	ds_read_b128 v[212:215], v202 offset:21504
	ds_read_b128 v[216:219], v202 offset:22528
	ds_read_b128 v[220:223], v202 offset:23552
	global_load_lds_dwordx4 v[196:197], off
	s_add_i32 m0, s64, 0x2000
	v_lshl_add_u64 v[224:225], s[62:63], 0, v[178:179]
	s_add_u32 s62, s62, s6
	s_addc_u32 s63, s63, s7
	s_add_i32 s64, s53, s34
	global_load_lds_dwordx4 v[224:225], off
	v_lshl_add_u64 v[226:227], s[62:63], 0, v[174:175]
	s_mov_b32 m0, s64
	v_lshl_add_u64 v[228:229], s[62:63], 0, v[178:179]
	global_load_lds_dwordx4 v[226:227], off
	s_add_i32 m0, s64, 0x2000
	v_lshl_add_u64 v[230:231], s[26:27], 0, v[172:173]
	global_load_lds_dwordx4 v[228:229], off
	s_mov_b32 m0, s35
	v_lshl_add_u64 v[232:233], s[26:27], 0, v[176:177]
	global_load_lds_dwordx4 v[230:231], off
	s_mov_b32 m0, s36
	s_nop 0
	global_load_lds_dwordx4 v[232:233], off
	s_cmp_eq_u32 s99, 0
	s_cbranch_scc1 .Lmw8_2
	s_waitcnt vmcnt(24)
	s_mov_b32 s99, 0
	s_branch .Lmwj_2

; #define PG8_STAGE(bufoff, gbase, voff) do { _Pragma("unroll") for (int _i = 0; _i < 2; ++_i) \
;         __builtin_amdgcn_global_load_lds((const unsigned*)((const char*)(gbase) + (voff)[_i]), (PG8_LAS unsigned*)(lds + (bufoff) + ldsw + _i * 8192), 16, 0, 0); } while (0)
; #define PG8_LDA(dst, b, h) do { _Pragma("unroll") for (int m = 0; m < 4; ++m) _Pragma("unroll") for (int k = 0; k < 2; ++k) dst[m][k] = *(const PG8_LAS bf16x8*)(lds + PG8_SA(b, h) + aoff + m * 2048 + k * 1024); } while (0)
; #define PG8_LDB(dst, b, h) do { _Pragma("unroll") for (int n = 0; n < 2; ++n) _Pragma("unroll") for (int k = 0; k < 2; ++k) dst[n][k] = *(const PG8_LAS bf16x8*)(lds + PG8_SB(b, h) + boff + n * 2048 + k * 1024); } while (0)
; #define PG8_MMA(ai, bj, At, Bt) do { __builtin_amdgcn_s_setprio(1); _Pragma("unroll") for (int m = 0; m < 4; ++m) _Pragma("unroll") for (int n = 0; n < 2; ++n) _Pragma("unroll") for (int k = 0; k < 2; ++k) \
;         acc[ai][bj][m][n] = __builtin_amdgcn_mfma_f32_16x16x32_bf16(Bt[n][k], At[m][k], acc[ai][bj][m][n], 0, 0, 0); __builtin_amdgcn_s_setprio(0); } while (0)
; #define PG8_WAIT_V(n) asm volatile("s_waitcnt vmcnt(" #n ")" ::: "memory")
; #define PG8_WAIT_L(n) asm volatile("s_waitcnt lgkmcnt(" #n ")" ::: "memory")
; #define PG8_BAR __builtin_amdgcn_s_barrier()
; #define PG8_SCHED __builtin_amdgcn_sched_barrier(0)
; template <class Epi, class Sched, bool ALIGN_EPI = false, bool SP2 = false>
; __device__ __forceinline__ void gemm_phase(PG8_LAS unsigned char* lds, const Gemm g, const Sched& S, const Epi& E) {
;     ...
;             PG8_WAIT_V(8); PG8_WAIT_L(0); PG8_BAR; PG8_MMA(1, 0, At, B0); PG8_MMA(1, 1, At, B1); PG8_BAR; PG8_SCHED;
;             PG8_LDB(B0, 1, 0); PG8_LDB(B1, 1, 1); PG8_SCHED; PG8_LDA(At, 1, 0); PG8_STAGE(PG8_SA(0, 1), a2 + hstep, voffA);
;             PG8_WAIT_V(8); PG8_WAIT_L(0); PG8_BAR; PG8_MMA(0, 0, At, B0); PG8_MMA(0, 1, At, B1); PG8_BAR; PG8_SCHED;
.Lmwj_2:
	s_waitcnt lgkmcnt(0)
	s_barrier
	s_setprio 1
	s_waitcnt lgkmcnt(0)
	v_mfma_f32_16x16x32_bf16 v[64:67], v[132:135], v[164:167], v[64:67]
	v_mfma_f32_16x16x32_bf16 v[60:63], v[140:143], v[164:167], v[60:63]
	v_mfma_f32_16x16x32_bf16 v[48:51], v[132:135], v[192:195], v[48:51]
	v_mfma_f32_16x16x32_bf16 v[44:47], v[140:143], v[192:195], v[44:47]
	v_mfma_f32_16x16x32_bf16 v[32:35], v[132:135], v[208:211], v[32:35]
	v_mfma_f32_16x16x32_bf16 v[28:31], v[140:143], v[208:211], v[28:31]
	v_mfma_f32_16x16x32_bf16 v[16:19], v[132:135], v[216:219], v[16:19]
	v_mfma_f32_16x16x32_bf16 v[12:15], v[140:143], v[216:219], v[12:15]
	v_mfma_f32_16x16x32_bf16 v[64:67], v[136:139], v[188:191], v[64:67]
	v_mfma_f32_16x16x32_bf16 v[60:63], v[144:147], v[188:191], v[60:63]
	v_mfma_f32_16x16x32_bf16 v[48:51], v[136:139], v[204:207], v[48:51]
	v_mfma_f32_16x16x32_bf16 v[44:47], v[144:147], v[204:207], v[44:47]
	v_mfma_f32_16x16x32_bf16 v[32:35], v[136:139], v[212:215], v[32:35]
	v_mfma_f32_16x16x32_bf16 v[28:31], v[144:147], v[212:215], v[28:31]
	v_mfma_f32_16x16x32_bf16 v[16:19], v[136:139], v[220:223], v[16:19]
	v_mfma_f32_16x16x32_bf16 v[12:15], v[144:147], v[220:223], v[12:15]
	s_setprio 0
	s_setprio 1
	v_mfma_f32_16x16x32_bf16 v[56:59], v[148:151], v[164:167], v[56:59]
	v_mfma_f32_16x16x32_bf16 v[52:55], v[156:159], v[164:167], v[52:55]
	v_mfma_f32_16x16x32_bf16 v[40:43], v[148:151], v[192:195], v[40:43]
	v_mfma_f32_16x16x32_bf16 v[36:39], v[156:159], v[192:195], v[36:39]
	v_mfma_f32_16x16x32_bf16 v[24:27], v[148:151], v[208:211], v[24:27]
	v_mfma_f32_16x16x32_bf16 v[20:23], v[156:159], v[208:211], v[20:23]
	v_mfma_f32_16x16x32_bf16 v[8:11], v[148:151], v[216:219], v[8:11]
	v_mfma_f32_16x16x32_bf16 v[2:5], v[156:159], v[216:219], v[4:7]
	v_mfma_f32_16x16x32_bf16 v[56:59], v[152:155], v[188:191], v[56:59]
	v_mfma_f32_16x16x32_bf16 v[52:55], v[160:163], v[188:191], v[52:55]
	v_mfma_f32_16x16x32_bf16 v[40:43], v[152:155], v[204:207], v[40:43]
	v_mfma_f32_16x16x32_bf16 v[36:39], v[160:163], v[204:207], v[36:39]
	v_mfma_f32_16x16x32_bf16 v[24:27], v[152:155], v[212:215], v[24:27]
	v_mfma_f32_16x16x32_bf16 v[20:23], v[160:163], v[212:215], v[20:23]
	v_mfma_f32_16x16x32_bf16 v[8:11], v[152:155], v[220:223], v[8:11]
	v_mfma_f32_16x16x32_bf16 v[2:5], v[160:163], v[220:223], v[2:5]
	s_setprio 0
	s_barrier
	s_add_i32 s62, 0, 0x18000
	v_add_u32_e32 v1, s62, v201
	s_add_i32 s63, 0, 0x1c000
	ds_read_b128 v[132:135], v1
	ds_read_b128 v[136:139], v1 offset:1024
	ds_read_b128 v[140:143], v1 offset:2048
	ds_read_b128 v[144:147], v1 offset:3072
	v_add_u32_e32 v1, s63, v201
	ds_read_b128 v[148:151], v1
	ds_read_b128 v[152:155], v1 offset:1024
	ds_read_b128 v[156:159], v1 offset:2048
	ds_read_b128 v[160:163], v1 offset:3072
	s_add_u32 s26, s26, s6
	s_addc_u32 s27, s27, s7
	s_mov_b32 m0, s37
	v_lshl_add_u64 v[6:7], s[26:27], 0, v[172:173]
	ds_read_b128 v[164:167], v202 offset:32768
	ds_read_b128 v[188:191], v202 offset:33792
	ds_read_b128 v[192:195], v202 offset:34816
	ds_read_b128 v[204:207], v202 offset:35840
	ds_read_b128 v[208:211], v202 offset:36864
	ds_read_b128 v[212:215], v202 offset:37888
	ds_read_b128 v[216:219], v202 offset:38912
	ds_read_b128 v[220:223], v202 offset:39936
	global_load_lds_dwordx4 v[6:7], off
	v_lshl_add_u64 v[6:7], s[26:27], 0, v[176:177]
	s_mov_b32 m0, s38
	s_nop 0
	global_load_lds_dwordx4 v[6:7], off
	s_waitcnt vmcnt(8)
	s_waitcnt lgkmcnt(0)
	s_barrier
	s_setprio 1
	s_waitcnt lgkmcnt(0)
	v_mfma_f32_16x16x32_bf16 v[116:119], v[132:135], v[164:167], v[116:119]
	v_mfma_f32_16x16x32_bf16 v[120:123], v[140:143], v[164:167], v[120:123]
	v_mfma_f32_16x16x32_bf16 v[112:115], v[132:135], v[192:195], v[112:115]
	v_mfma_f32_16x16x32_bf16 v[108:111], v[140:143], v[192:195], v[108:111]
	v_mfma_f32_16x16x32_bf16 v[96:99], v[132:135], v[208:211], v[96:99]
	v_mfma_f32_16x16x32_bf16 v[92:95], v[140:143], v[208:211], v[92:95]
	v_mfma_f32_16x16x32_bf16 v[80:83], v[132:135], v[216:219], v[80:83]
	v_mfma_f32_16x16x32_bf16 v[76:79], v[140:143], v[216:219], v[76:79]
	v_mfma_f32_16x16x32_bf16 v[116:119], v[136:139], v[188:191], v[116:119]
	v_mfma_f32_16x16x32_bf16 v[120:123], v[144:147], v[188:191], v[120:123]
	v_mfma_f32_16x16x32_bf16 v[112:115], v[136:139], v[204:207], v[112:115]
	v_mfma_f32_16x16x32_bf16 v[108:111], v[144:147], v[204:207], v[108:111]
	v_mfma_f32_16x16x32_bf16 v[96:99], v[136:139], v[212:215], v[96:99]
	v_mfma_f32_16x16x32_bf16 v[92:95], v[144:147], v[212:215], v[92:95]
	v_mfma_f32_16x16x32_bf16 v[80:83], v[136:139], v[220:223], v[80:83]
	v_mfma_f32_16x16x32_bf16 v[76:79], v[144:147], v[220:223], v[76:79]
	s_setprio 0
	s_setprio 1
	v_mfma_f32_16x16x32_bf16 v[128:131], v[148:151], v[164:167], v[128:131]
	v_mfma_f32_16x16x32_bf16 v[124:127], v[156:159], v[164:167], v[124:127]
	v_mfma_f32_16x16x32_bf16 v[104:107], v[148:151], v[192:195], v[104:107]
	v_mfma_f32_16x16x32_bf16 v[100:103], v[156:159], v[192:195], v[100:103]
	v_mfma_f32_16x16x32_bf16 v[88:91], v[148:151], v[208:211], v[88:91]
	v_mfma_f32_16x16x32_bf16 v[84:87], v[156:159], v[208:211], v[84:87]
	v_mfma_f32_16x16x32_bf16 v[72:75], v[148:151], v[216:219], v[72:75]
	v_mfma_f32_16x16x32_bf16 v[68:71], v[156:159], v[216:219], v[68:71]
	v_mfma_f32_16x16x32_bf16 v[128:131], v[152:155], v[188:191], v[128:131]
	v_mfma_f32_16x16x32_bf16 v[124:127], v[160:163], v[188:191], v[124:127]
	v_mfma_f32_16x16x32_bf16 v[104:107], v[152:155], v[204:207], v[104:107]
	v_mfma_f32_16x16x32_bf16 v[100:103], v[160:163], v[204:207], v[100:103]
	v_mfma_f32_16x16x32_bf16 v[88:91], v[152:155], v[212:215], v[88:91]
	v_mfma_f32_16x16x32_bf16 v[84:87], v[160:163], v[212:215], v[84:87]
	v_mfma_f32_16x16x32_bf16 v[72:75], v[152:155], v[220:223], v[72:75]
	v_mfma_f32_16x16x32_bf16 v[68:71], v[160:163], v[220:223], v[68:71]
	s_setprio 0
	s_barrier
; #define PG8_STAGE(bufoff, gbase, voff) do { _Pragma("unroll") for (int _i = 0; _i < 2; ++_i) \
;         __builtin_amdgcn_global_load_lds((const unsigned*)((const char*)(gbase) + (voff)[_i]), (PG8_LAS unsigned*)(lds + (bufoff) + ldsw + _i * 8192), 16, 0, 0); } while (0)
; #define PG8_LDA(dst, b, h) do { _Pragma("unroll") for (int m = 0; m < 4; ++m) _Pragma("unroll") for (int k = 0; k < 2; ++k) dst[m][k] = *(const PG8_LAS bf16x8*)(lds + PG8_SA(b, h) + aoff + m * 2048 + k * 1024); } while (0)
; #define PG8_MMA(ai, bj, At, Bt) do { __builtin_amdgcn_s_setprio(1); _Pragma("unroll") for (int m = 0; m < 4; ++m) _Pragma("unroll") for (int n = 0; n < 2; ++n) _Pragma("unroll") for (int k = 0; k < 2; ++k) \
;         acc[ai][bj][m][n] = __builtin_amdgcn_mfma_f32_16x16x32_bf16(Bt[n][k], At[m][k], acc[ai][bj][m][n], 0, 0, 0); __builtin_amdgcn_s_setprio(0); } while (0)
; #define PG8_WAIT_V(n) asm volatile("s_waitcnt vmcnt(" #n ")" ::: "memory")
; #define PG8_WAIT_L(n) asm volatile("s_waitcnt lgkmcnt(" #n ")" ::: "memory")
; #define PG8_BAR __builtin_amdgcn_s_barrier()
; #define PG8_SCHED __builtin_amdgcn_sched_barrier(0)
; template <class Epi, class Sched, bool ALIGN_EPI = false, bool SP2 = false>
; __device__ __forceinline__ void gemm_phase(PG8_LAS unsigned char* lds, const Gemm g, const Sched& S, const Epi& E) {
;     ...
;         for (int t = 0; t < nt; t += 2) {
;     ...
;             PG8_LDA(At, 1, 1); PG8_STAGE(PG8_SB(1, 0), b3, voffB); PG8_STAGE(PG8_SB(1, 1), b3 + hstep, voffB); PG8_STAGE(PG8_SA(1, 0), a3, voffA);
;             PG8_WAIT_V(8); PG8_WAIT_L(0); PG8_BAR; PG8_MMA(1, 0, At, B0); PG8_MMA(1, 1, At, B1); PG8_BAR; PG8_SCHED;
	s_add_i32 s26, s62, s34
	v_lshl_add_u64 v[6:7], v[196:197], 0, s[12:13]
	s_mov_b32 m0, s26
	ds_read_b128 v[164:167], v202 offset:49152
	ds_read_b128 v[188:191], v202 offset:50176
	ds_read_b128 v[192:195], v202 offset:51200
	ds_read_b128 v[204:207], v202 offset:52224
	ds_read_b128 v[208:211], v202 offset:53248
	ds_read_b128 v[212:215], v202 offset:54272
	ds_read_b128 v[216:219], v202 offset:55296
	ds_read_b128 v[220:223], v202 offset:56320
	global_load_lds_dwordx4 v[6:7], off
	v_lshl_add_u64 v[6:7], v[224:225], 0, s[12:13]
	s_add_i32 m0, s26, 0x2000
	s_add_i32 s26, s63, s34
	global_load_lds_dwordx4 v[6:7], off
	v_lshl_add_u64 v[6:7], v[226:227], 0, s[12:13]
	s_mov_b32 m0, s26
	s_nop 0
	global_load_lds_dwordx4 v[6:7], off
	v_lshl_add_u64 v[6:7], v[228:229], 0, s[12:13]
	s_add_i32 m0, s26, 0x2000
	s_nop 0
	global_load_lds_dwordx4 v[6:7], off
	v_lshl_add_u64 v[6:7], v[230:231], 0, s[12:13]
	s_mov_b32 m0, s40
	s_nop 0
	global_load_lds_dwordx4 v[6:7], off
	v_lshl_add_u64 v[6:7], v[232:233], 0, s[12:13]
	s_mov_b32 m0, s41
	s_nop 0
	global_load_lds_dwordx4 v[6:7], off
	s_waitcnt vmcnt(8)
	s_waitcnt lgkmcnt(0)
	s_barrier
	s_setprio 1
	s_waitcnt lgkmcnt(0)
	v_mfma_f32_16x16x32_bf16 v[64:67], v[132:135], v[164:167], v[64:67]
	v_mfma_f32_16x16x32_bf16 v[60:63], v[140:143], v[164:167], v[60:63]
	v_mfma_f32_16x16x32_bf16 v[48:51], v[132:135], v[192:195], v[48:51]
	v_mfma_f32_16x16x32_bf16 v[44:47], v[140:143], v[192:195], v[44:47]
	v_mfma_f32_16x16x32_bf16 v[32:35], v[132:135], v[208:211], v[32:35]
	v_mfma_f32_16x16x32_bf16 v[28:31], v[140:143], v[208:211], v[28:31]
	v_mfma_f32_16x16x32_bf16 v[16:19], v[132:135], v[216:219], v[16:19]
	v_mfma_f32_16x16x32_bf16 v[12:15], v[140:143], v[216:219], v[12:15]
	v_mfma_f32_16x16x32_bf16 v[64:67], v[136:139], v[188:191], v[64:67]
	v_mfma_f32_16x16x32_bf16 v[60:63], v[144:147], v[188:191], v[60:63]
	v_mfma_f32_16x16x32_bf16 v[48:51], v[136:139], v[204:207], v[48:51]
	v_mfma_f32_16x16x32_bf16 v[44:47], v[144:147], v[204:207], v[44:47]
	v_mfma_f32_16x16x32_bf16 v[32:35], v[136:139], v[212:215], v[32:35]
	v_mfma_f32_16x16x32_bf16 v[28:31], v[144:147], v[212:215], v[28:31]
	v_mfma_f32_16x16x32_bf16 v[16:19], v[136:139], v[220:223], v[16:19]
	v_mfma_f32_16x16x32_bf16 v[12:15], v[144:147], v[220:223], v[12:15]
	s_setprio 0
	s_setprio 1
	v_mfma_f32_16x16x32_bf16 v[56:59], v[148:151], v[164:167], v[56:59]
	v_mfma_f32_16x16x32_bf16 v[52:55], v[156:159], v[164:167], v[52:55]
	v_mfma_f32_16x16x32_bf16 v[40:43], v[148:151], v[192:195], v[40:43]
	v_mfma_f32_16x16x32_bf16 v[36:39], v[156:159], v[192:195], v[36:39]
	v_mfma_f32_16x16x32_bf16 v[24:27], v[148:151], v[208:211], v[24:27]
	v_mfma_f32_16x16x32_bf16 v[20:23], v[156:159], v[208:211], v[20:23]
	v_mfma_f32_16x16x32_bf16 v[6:9], v[148:151], v[216:219], v[8:11]
	v_mfma_f32_16x16x32_bf16 v[2:5], v[156:159], v[216:219], v[2:5]
	v_mfma_f32_16x16x32_bf16 v[56:59], v[152:155], v[188:191], v[56:59]
	v_mfma_f32_16x16x32_bf16 v[52:55], v[160:163], v[188:191], v[52:55]
	v_mfma_f32_16x16x32_bf16 v[40:43], v[152:155], v[204:207], v[40:43]
	v_mfma_f32_16x16x32_bf16 v[36:39], v[160:163], v[204:207], v[36:39]
	v_mfma_f32_16x16x32_bf16 v[24:27], v[152:155], v[212:215], v[24:27]
	v_mfma_f32_16x16x32_bf16 v[20:23], v[160:163], v[212:215], v[20:23]
	v_mfma_f32_16x16x32_bf16 v[8:11], v[152:155], v[220:223], v[6:9]
	v_mfma_f32_16x16x32_bf16 v[4:7], v[160:163], v[220:223], v[2:5]
	s_setprio 0
	s_barrier
	s_add_u32 s24, s24, 0x100
	s_addc_u32 s25, s25, 0
	s_cmp_ge_i32 s61, s42
	s_cbranch_scc1 .LBB0_1314
	s_mov_b32 s26, s61
	s_cmp_lg_u32 s26, 16
	s_cbranch_scc0 .LBB0_1311
	s_branch .LBB0_1312

; __device__ __forceinline__ u32x4 pk8(f32x4 a, f32x4 b) { u32x4 w; w.x = pk2(a[0], a[1]); w.y = pk2(a[2], a[3]); w.z = pk2(b[0], b[1]); w.w = pk2(b[2], b[3]); return w; }
; __device__ __forceinline__ float bf_lo(unsigned w) { return __uint_as_float(w << 16); }
; __device__ __forceinline__ float bf_hi(unsigned w) { return __uint_as_float(w & 0xffff0000u); }
;     __device__ __forceinline__ void operator()(const AccT& acc, const Unit& u, int wr, int wc, int fr_, int fq_) const {
;         int fr = fr_, fq = fq_; asm volatile("" : "+v"(fr), "+v"(fq));
;         const bf16_t* const SB = (const bf16_t*)out + (size_t)T * 1024; bf16_t* const M = (bf16_t*)(ws + WS_RA);
;         u32x4 w[2][4][2];
; #pragma unroll
;         for (int ai = 0; ai < 2; ++ai)
; #pragma unroll
;             for (int m = 0; m < 4; ++m)
; #pragma unroll
;                 for (int bj = 0; bj < 2; ++bj) w[ai][m][bj] = *(const u32x4*)(SB + (size_t)ROW_OF(ai, m) * 1024 + u.pn * 256 + bj * 128 + wc * 32 + 8 * fq);
; #pragma unroll
;         for (int ai = 0; ai < 2; ++ai)
; #pragma unroll
;             for (int m = 0; m < 4; ++m)
; #pragma unroll
;                 for (int bj = 0; bj < 2; ++bj) { const u32x4 v = w[ai][m][bj];
;                     const size_t off = (size_t)ROW_OF(ai, m) * 1024 + u.pn * 256 + bj * 128 + wc * 32 + 8 * fq;
;                     const f32x4 v0 = acc[ai][bj][m][0] * (f32x4){bf_lo(v.x), bf_hi(v.x), bf_lo(v.y), bf_hi(v.y)};
;                     const f32x4 v1 = acc[ai][bj][m][1] * (f32x4){bf_lo(v.z), bf_hi(v.z), bf_lo(v.w), bf_hi(v.w)};
;                     st16c(M + off, pk8(v0, v1)); }
.LBB0_1316:
	s_mov_b32 s99, 1
	s_lshl_b32 s20, s56, 8
	v_mov_b32_e32 v1, v198
	v_mov_b32_e32 v3, v199
	s_add_i32 s20, s20, s43
	s_nop 0
	v_add_u32_e32 v2, s20, v1
	s_lshl_b32 s20, s57, 8
	s_ashr_i32 s21, s20, 31
	s_lshl_b64 s[20:21], s[20:21], 1
	v_lshlrev_b32_e32 v132, 3, v3
	s_add_u32 s22, s47, s20
	v_ashrrev_i32_e32 v133, 31, v132
	s_addc_u32 s23, s48, s21
	v_lshlrev_b64 v[188:189], 1, v[132:133]
	v_ashrrev_i32_e32 v3, 31, v2
	v_lshl_add_u64 v[132:133], s[22:23], 0, v[188:189]
	v_lshlrev_b64 v[228:229], 11, v[2:3]
	v_lshl_add_u64 v[134:135], v[132:133], 0, v[228:229]
	global_load_dwordx4 v[204:207], v[134:135], off
	global_load_dwordx4 v[208:211], v[134:135], off offset:256
	v_add_u32_e32 v134, 16, v2
	v_ashrrev_i32_e32 v135, 31, v134
	v_lshlrev_b64 v[230:231], 11, v[134:135]
	v_lshl_add_u64 v[134:135], v[132:133], 0, v[230:231]
	global_load_dwordx4 v[212:215], v[134:135], off
	global_load_dwordx4 v[216:219], v[134:135], off offset:256
	v_add_u32_e32 v136, 32, v2
	v_add_u32_e32 v138, 48, v2
	v_add_u32_e32 v140, 0x80, v2
	v_add_u32_e32 v142, 0x90, v2
	v_add_u32_e32 v144, 0xa0, v2
	v_add_u32_e32 v2, 0xb0, v2
	v_ashrrev_i32_e32 v137, 31, v136
	v_ashrrev_i32_e32 v139, 31, v138
	v_ashrrev_i32_e32 v141, 31, v140
	v_ashrrev_i32_e32 v143, 31, v142
	v_ashrrev_i32_e32 v145, 31, v144
	v_ashrrev_i32_e32 v3, 31, v2
	v_lshlrev_b64 v[232:233], 11, v[136:137]
	v_lshlrev_b64 v[196:197], 11, v[138:139]
	v_lshlrev_b64 v[194:195], 11, v[140:141]
	v_lshlrev_b64 v[192:193], 11, v[142:143]
	v_lshlrev_b64 v[190:191], 11, v[144:145]
	v_lshlrev_b64 v[2:3], 11, v[2:3]
	v_lshl_add_u64 v[134:135], v[132:133], 0, v[232:233]
	v_lshl_add_u64 v[136:137], v[132:133], 0, v[196:197]
	v_lshl_add_u64 v[138:139], v[132:133], 0, v[194:195]
	v_lshl_add_u64 v[140:141], v[132:133], 0, v[192:193]
	v_lshl_add_u64 v[142:143], v[132:133], 0, v[190:191]
	v_lshl_add_u64 v[132:133], v[132:133], 0, v[2:3]
	global_load_dwordx4 v[220:223], v[134:135], off
	global_load_dwordx4 v[224:227], v[134:135], off offset:256
	global_load_dwordx4 v[168:171], v[136:137], off
	global_load_dwordx4 v[164:167], v[136:137], off offset:256
	global_load_dwordx4 v[160:163], v[138:139], off
	global_load_dwordx4 v[156:159], v[138:139], off offset:256
	global_load_dwordx4 v[152:155], v[140:141], off
	global_load_dwordx4 v[148:151], v[140:141], off offset:256
	global_load_dwordx4 v[144:147], v[142:143], off
	s_nop 0
	global_load_dwordx4 v[140:143], v[142:143], off offset:256
	s_nop 0
	global_load_dwordx4 v[136:139], v[132:133], off
	s_nop 0
	global_load_dwordx4 v[132:135], v[132:133], off offset:256
	s_add_u32 s20, s49, s20
	s_addc_u32 s21, s50, s21
	v_lshl_add_u64 v[188:189], s[20:21], 0, v[188:189]
	v_lshl_add_u64 v[228:229], v[188:189], 0, v[228:229]
	s_and_b64 vcc, exec, s[2:3]
	s_mov_b64 s[2:3], -1
	s_waitcnt vmcnt(0)
	v_lshlrev_b32_e32 v234, 16, v204
	v_and_b32_e32 v235, 0xffff0000, v204
	v_lshlrev_b32_e32 v204, 16, v205
	v_and_b32_e32 v205, 0xffff0000, v205
	v_lshlrev_b32_e32 v236, 16, v206
	v_and_b32_e32 v237, 0xffff0000, v206
	v_lshlrev_b32_e32 v206, 16, v207
	v_and_b32_e32 v207, 0xffff0000, v207
	v_pk_mul_f32 v[118:119], v[118:119], v[204:205]
	v_pk_mul_f32 v[116:117], v[116:117], v[234:235]
	v_pk_mul_f32 v[122:123], v[122:123], v[206:207]
	v_pk_mul_f32 v[120:121], v[120:121], v[236:237]
	v_cvt_pk_bf16_f32 v116, v116, v117
	v_cvt_pk_bf16_f32 v117, v118, v119
	v_cvt_pk_bf16_f32 v118, v120, v121
	v_cvt_pk_bf16_f32 v119, v122, v123
	v_lshlrev_b32_e32 v238, 16, v208
	v_and_b32_e32 v239, 0xffff0000, v208
	v_lshlrev_b32_e32 v208, 16, v209
	v_and_b32_e32 v209, 0xffff0000, v209
	v_lshlrev_b32_e32 v240, 16, v210
	v_and_b32_e32 v241, 0xffff0000, v210
	global_store_dwordx4 v[228:229], v[116:119], off
	v_pk_mul_f32 v[130:131], v[130:131], v[208:209]
	v_pk_mul_f32 v[128:129], v[128:129], v[238:239]
	v_lshlrev_b32_e32 v116, 16, v211
	v_and_b32_e32 v117, 0xffff0000, v211
	v_pk_mul_f32 v[120:121], v[126:127], v[116:117]
	v_pk_mul_f32 v[118:119], v[124:125], v[240:241]
	v_cvt_pk_bf16_f32 v116, v128, v129
	v_cvt_pk_bf16_f32 v117, v130, v131
	v_cvt_pk_bf16_f32 v118, v118, v119
	v_cvt_pk_bf16_f32 v119, v120, v121
	global_store_dwordx4 v[228:229], v[116:119], off offset:256
	v_lshlrev_b32_e32 v120, 16, v213
	v_and_b32_e32 v121, 0xffff0000, v213
	v_lshlrev_b32_e32 v118, 16, v212
	v_and_b32_e32 v119, 0xffff0000, v212
	v_pk_mul_f32 v[114:115], v[114:115], v[120:121]
	v_pk_mul_f32 v[112:113], v[112:113], v[118:119]
	v_lshlrev_b32_e32 v118, 16, v214
	v_and_b32_e32 v119, 0xffff0000, v214
	v_lshlrev_b32_e32 v120, 16, v215
	v_and_b32_e32 v121, 0xffff0000, v215
	v_pk_mul_f32 v[120:121], v[110:111], v[120:121]
	v_pk_mul_f32 v[110:111], v[108:109], v[118:119]
	v_lshl_add_u64 v[116:117], v[188:189], 0, v[230:231]
	v_cvt_pk_bf16_f32 v108, v112, v113
	v_cvt_pk_bf16_f32 v109, v114, v115
	v_cvt_pk_bf16_f32 v110, v110, v111
	v_cvt_pk_bf16_f32 v111, v120, v121
	global_store_dwordx4 v[116:117], v[108:111], off
	s_nop 1
	v_lshlrev_b32_e32 v108, 16, v216
	v_and_b32_e32 v109, 0xffff0000, v216
	v_lshlrev_b32_e32 v110, 16, v217
	v_and_b32_e32 v111, 0xffff0000, v217
	v_pk_mul_f32 v[106:107], v[106:107], v[110:111]
	v_pk_mul_f32 v[104:105], v[104:105], v[108:109]
	v_lshlrev_b32_e32 v108, 16, v218
	v_and_b32_e32 v109, 0xffff0000, v218
	v_lshlrev_b32_e32 v110, 16, v219
	v_and_b32_e32 v111, 0xffff0000, v219
	v_pk_mul_f32 v[110:111], v[102:103], v[110:111]
	v_pk_mul_f32 v[102:103], v[100:101], v[108:109]
	v_cvt_pk_bf16_f32 v100, v104, v105
	v_cvt_pk_bf16_f32 v101, v106, v107
	v_cvt_pk_bf16_f32 v102, v102, v103
	v_cvt_pk_bf16_f32 v103, v110, v111
	global_store_dwordx4 v[116:117], v[100:103], off offset:256
	v_lshlrev_b32_e32 v104, 16, v221
; __device__ __forceinline__ u32x4 pk8(f32x4 a, f32x4 b) { u32x4 w; w.x = pk2(a[0], a[1]); w.y = pk2(a[2], a[3]); w.z = pk2(b[0], b[1]); w.w = pk2(b[2], b[3]); return w; }
; __device__ __forceinline__ float bf_lo(unsigned w) { return __uint_as_float(w << 16); }
; __device__ __forceinline__ float bf_hi(unsigned w) { return __uint_as_float(w & 0xffff0000u); }
;     __device__ __forceinline__ void operator()(const AccT& acc, const Unit& u, int wr, int wc, int fr_, int fq_) const {
;     ...
;         for (int ai = 0; ai < 2; ++ai)
; #pragma unroll
;             for (int m = 0; m < 4; ++m)
; #pragma unroll
;                 for (int bj = 0; bj < 2; ++bj) { const u32x4 v = w[ai][m][bj];
;                     const size_t off = (size_t)ROW_OF(ai, m) * 1024 + u.pn * 256 + bj * 128 + wc * 32 + 8 * fq;
;                     const f32x4 v0 = acc[ai][bj][m][0] * (f32x4){bf_lo(v.x), bf_hi(v.x), bf_lo(v.y), bf_hi(v.y)};
;                     const f32x4 v1 = acc[ai][bj][m][1] * (f32x4){bf_lo(v.z), bf_hi(v.z), bf_lo(v.w), bf_hi(v.w)};
;                     st16c(M + off, pk8(v0, v1)); }
	v_and_b32_e32 v105, 0xffff0000, v221
	v_lshlrev_b32_e32 v102, 16, v220
	v_and_b32_e32 v103, 0xffff0000, v220
	v_pk_mul_f32 v[98:99], v[98:99], v[104:105]
	v_pk_mul_f32 v[96:97], v[96:97], v[102:103]
	v_lshlrev_b32_e32 v102, 16, v222
	v_and_b32_e32 v103, 0xffff0000, v222
	v_lshlrev_b32_e32 v104, 16, v223
	v_and_b32_e32 v105, 0xffff0000, v223
	v_pk_mul_f32 v[104:105], v[94:95], v[104:105]
	v_pk_mul_f32 v[94:95], v[92:93], v[102:103]
	v_lshl_add_u64 v[100:101], v[188:189], 0, v[232:233]
	v_cvt_pk_bf16_f32 v92, v96, v97
	v_cvt_pk_bf16_f32 v93, v98, v99
	v_cvt_pk_bf16_f32 v94, v94, v95
	v_cvt_pk_bf16_f32 v95, v104, v105
	global_store_dwordx4 v[100:101], v[92:95], off
	s_nop 1
	v_lshlrev_b32_e32 v92, 16, v224
	v_and_b32_e32 v93, 0xffff0000, v224
	v_lshlrev_b32_e32 v94, 16, v225
	v_and_b32_e32 v95, 0xffff0000, v225
	v_pk_mul_f32 v[90:91], v[90:91], v[94:95]
	v_pk_mul_f32 v[88:89], v[88:89], v[92:93]
	v_lshlrev_b32_e32 v92, 16, v226
	v_and_b32_e32 v93, 0xffff0000, v226
	v_lshlrev_b32_e32 v94, 16, v227
	v_and_b32_e32 v95, 0xffff0000, v227
	v_pk_mul_f32 v[94:95], v[86:87], v[94:95]
	v_pk_mul_f32 v[86:87], v[84:85], v[92:93]
	v_cvt_pk_bf16_f32 v84, v88, v89
	v_cvt_pk_bf16_f32 v85, v90, v91
	v_cvt_pk_bf16_f32 v86, v86, v87
	v_cvt_pk_bf16_f32 v87, v94, v95
	global_store_dwordx4 v[100:101], v[84:87], off offset:256
	v_lshlrev_b32_e32 v88, 16, v169
	v_and_b32_e32 v89, 0xffff0000, v169
	v_lshlrev_b32_e32 v86, 16, v168
	v_and_b32_e32 v87, 0xffff0000, v168
	v_pk_mul_f32 v[82:83], v[82:83], v[88:89]
	v_pk_mul_f32 v[80:81], v[80:81], v[86:87]
	v_lshlrev_b32_e32 v86, 16, v170
	v_and_b32_e32 v87, 0xffff0000, v170
	v_lshlrev_b32_e32 v88, 16, v171
	v_and_b32_e32 v89, 0xffff0000, v171
	v_pk_mul_f32 v[88:89], v[78:79], v[88:89]
	v_pk_mul_f32 v[78:79], v[76:77], v[86:87]
	v_lshl_add_u64 v[84:85], v[188:189], 0, v[196:197]
	v_cvt_pk_bf16_f32 v76, v80, v81
	v_cvt_pk_bf16_f32 v77, v82, v83
	v_cvt_pk_bf16_f32 v78, v78, v79
	v_cvt_pk_bf16_f32 v79, v88, v89
	global_store_dwordx4 v[84:85], v[76:79], off
	s_nop 1
	v_lshlrev_b32_e32 v76, 16, v164
	v_and_b32_e32 v77, 0xffff0000, v164
	v_lshlrev_b32_e32 v78, 16, v165
	v_and_b32_e32 v79, 0xffff0000, v165
	v_pk_mul_f32 v[74:75], v[74:75], v[78:79]
	v_pk_mul_f32 v[72:73], v[72:73], v[76:77]
	v_lshlrev_b32_e32 v76, 16, v166
	v_and_b32_e32 v77, 0xffff0000, v166
	v_lshlrev_b32_e32 v78, 16, v167
	v_and_b32_e32 v79, 0xffff0000, v167
	v_pk_mul_f32 v[78:79], v[70:71], v[78:79]
	v_pk_mul_f32 v[70:71], v[68:69], v[76:77]
	v_cvt_pk_bf16_f32 v68, v72, v73
	v_cvt_pk_bf16_f32 v69, v74, v75
	v_cvt_pk_bf16_f32 v70, v70, v71
	v_cvt_pk_bf16_f32 v71, v78, v79
	global_store_dwordx4 v[84:85], v[68:71], off offset:256
	v_lshlrev_b32_e32 v72, 16, v161
	v_and_b32_e32 v73, 0xffff0000, v161
	v_lshlrev_b32_e32 v70, 16, v160
	v_and_b32_e32 v71, 0xffff0000, v160
	v_pk_mul_f32 v[66:67], v[66:67], v[72:73]
	v_pk_mul_f32 v[64:65], v[64:65], v[70:71]
	v_lshlrev_b32_e32 v70, 16, v162
	v_and_b32_e32 v71, 0xffff0000, v162
	v_lshlrev_b32_e32 v72, 16, v163
	v_and_b32_e32 v73, 0xffff0000, v163
	v_pk_mul_f32 v[72:73], v[62:63], v[72:73]
	v_pk_mul_f32 v[62:63], v[60:61], v[70:71]
	v_lshl_add_u64 v[68:69], v[188:189], 0, v[194:195]
	v_cvt_pk_bf16_f32 v60, v64, v65
	v_cvt_pk_bf16_f32 v61, v66, v67
	v_cvt_pk_bf16_f32 v62, v62, v63
	v_cvt_pk_bf16_f32 v63, v72, v73
	global_store_dwordx4 v[68:69], v[60:63], off
	s_nop 1
	v_lshlrev_b32_e32 v60, 16, v156
	v_and_b32_e32 v61, 0xffff0000, v156
	v_lshlrev_b32_e32 v62, 16, v157
	v_and_b32_e32 v63, 0xffff0000, v157
	v_pk_mul_f32 v[58:59], v[58:59], v[62:63]
	v_pk_mul_f32 v[56:57], v[56:57], v[60:61]
	v_lshlrev_b32_e32 v60, 16, v158
	v_and_b32_e32 v61, 0xffff0000, v158
	v_lshlrev_b32_e32 v62, 16, v159
	v_and_b32_e32 v63, 0xffff0000, v159
	v_pk_mul_f32 v[62:63], v[54:55], v[62:63]
	v_pk_mul_f32 v[54:55], v[52:53], v[60:61]
	v_cvt_pk_bf16_f32 v52, v56, v57
	v_cvt_pk_bf16_f32 v53, v58, v59
	v_cvt_pk_bf16_f32 v54, v54, v55
	v_cvt_pk_bf16_f32 v55, v62, v63
	global_store_dwordx4 v[68:69], v[52:55], off offset:256
	v_lshlrev_b32_e32 v56, 16, v153
; #define PG8_BAR __builtin_amdgcn_s_barrier()
; __device__ __forceinline__ u32x4 pk8(f32x4 a, f32x4 b) { u32x4 w; w.x = pk2(a[0], a[1]); w.y = pk2(a[2], a[3]); w.z = pk2(b[0], b[1]); w.w = pk2(b[2], b[3]); return w; }
; __device__ __forceinline__ float bf_lo(unsigned w) { return __uint_as_float(w << 16); }
; __device__ __forceinline__ float bf_hi(unsigned w) { return __uint_as_float(w & 0xffff0000u); }
; template <class Epi, class Sched, bool ALIGN_EPI = false, bool SP2 = false>
; __device__ __forceinline__ void gemm_phase(PG8_LAS unsigned char* lds, const Gemm g, const Sched& S, const Epi& E) {
;     ...
;         if (!has_next) break;
; #pragma unroll
;         for (int a = 0; a < 2; ++a)
; #pragma unroll
;             for (int b = 0; b < 2; ++b)
; #pragma unroll
;                 for (int m = 0; m < 4; ++m)
; #pragma unroll
;                     for (int n = 0; n < 2; ++n) acc[a][b][m][n] = (f32x4){0.f, 0.f, 0.f, 0.f};
;         cur = nxt; cA = nA; cB = nB; ++ui;
;         if constexpr (ALIGN_EPI) { if (wr == 1) PG8_BAR; }
;     __device__ __forceinline__ void operator()(const AccT& acc, const Unit& u, int wr, int wc, int fr_, int fq_) const {
;     ...
;         for (int ai = 0; ai < 2; ++ai)
; #pragma unroll
;             for (int m = 0; m < 4; ++m)
; #pragma unroll
;                 for (int bj = 0; bj < 2; ++bj) { const u32x4 v = w[ai][m][bj];
;                     const size_t off = (size_t)ROW_OF(ai, m) * 1024 + u.pn * 256 + bj * 128 + wc * 32 + 8 * fq;
;                     const f32x4 v0 = acc[ai][bj][m][0] * (f32x4){bf_lo(v.x), bf_hi(v.x), bf_lo(v.y), bf_hi(v.y)};
;                     const f32x4 v1 = acc[ai][bj][m][1] * (f32x4){bf_lo(v.z), bf_hi(v.z), bf_lo(v.w), bf_hi(v.w)};
;                     st16c(M + off, pk8(v0, v1)); }
	v_and_b32_e32 v57, 0xffff0000, v153
	v_lshlrev_b32_e32 v54, 16, v152
	v_and_b32_e32 v55, 0xffff0000, v152
	v_pk_mul_f32 v[50:51], v[50:51], v[56:57]
	v_pk_mul_f32 v[48:49], v[48:49], v[54:55]
	v_lshlrev_b32_e32 v54, 16, v154
	v_and_b32_e32 v55, 0xffff0000, v154
	v_lshlrev_b32_e32 v56, 16, v155
	v_and_b32_e32 v57, 0xffff0000, v155
	v_pk_mul_f32 v[56:57], v[46:47], v[56:57]
	v_pk_mul_f32 v[46:47], v[44:45], v[54:55]
	v_lshl_add_u64 v[52:53], v[188:189], 0, v[192:193]
	v_cvt_pk_bf16_f32 v44, v48, v49
	v_cvt_pk_bf16_f32 v45, v50, v51
	v_cvt_pk_bf16_f32 v46, v46, v47
	v_cvt_pk_bf16_f32 v47, v56, v57
	global_store_dwordx4 v[52:53], v[44:47], off
	s_nop 1
	v_lshlrev_b32_e32 v44, 16, v148
	v_and_b32_e32 v45, 0xffff0000, v148
	v_lshlrev_b32_e32 v46, 16, v149
	v_and_b32_e32 v47, 0xffff0000, v149
	v_pk_mul_f32 v[42:43], v[42:43], v[46:47]
	v_pk_mul_f32 v[40:41], v[40:41], v[44:45]
	v_lshlrev_b32_e32 v44, 16, v150
	v_and_b32_e32 v45, 0xffff0000, v150
	v_lshlrev_b32_e32 v46, 16, v151
	v_and_b32_e32 v47, 0xffff0000, v151
	v_pk_mul_f32 v[46:47], v[38:39], v[46:47]
	v_pk_mul_f32 v[38:39], v[36:37], v[44:45]
	v_cvt_pk_bf16_f32 v36, v40, v41
	v_cvt_pk_bf16_f32 v37, v42, v43
	v_cvt_pk_bf16_f32 v38, v38, v39
	v_cvt_pk_bf16_f32 v39, v46, v47
	global_store_dwordx4 v[52:53], v[36:39], off offset:256
	v_lshlrev_b32_e32 v40, 16, v145
	v_and_b32_e32 v41, 0xffff0000, v145
	v_lshlrev_b32_e32 v38, 16, v144
	v_and_b32_e32 v39, 0xffff0000, v144
	v_pk_mul_f32 v[34:35], v[34:35], v[40:41]
	v_pk_mul_f32 v[32:33], v[32:33], v[38:39]
	v_lshlrev_b32_e32 v38, 16, v146
	v_and_b32_e32 v39, 0xffff0000, v146
	v_lshlrev_b32_e32 v40, 16, v147
	v_and_b32_e32 v41, 0xffff0000, v147
	v_pk_mul_f32 v[40:41], v[30:31], v[40:41]
	v_pk_mul_f32 v[30:31], v[28:29], v[38:39]
	v_lshl_add_u64 v[36:37], v[188:189], 0, v[190:191]
	v_cvt_pk_bf16_f32 v28, v32, v33
	v_cvt_pk_bf16_f32 v29, v34, v35
	v_cvt_pk_bf16_f32 v30, v30, v31
	v_cvt_pk_bf16_f32 v31, v40, v41
	global_store_dwordx4 v[36:37], v[28:31], off
	s_nop 1
	v_lshlrev_b32_e32 v28, 16, v140
	v_and_b32_e32 v29, 0xffff0000, v140
	v_lshlrev_b32_e32 v30, 16, v141
	v_and_b32_e32 v31, 0xffff0000, v141
	v_pk_mul_f32 v[26:27], v[26:27], v[30:31]
	v_pk_mul_f32 v[24:25], v[24:25], v[28:29]
	v_lshlrev_b32_e32 v28, 16, v142
	v_and_b32_e32 v29, 0xffff0000, v142
	v_lshlrev_b32_e32 v30, 16, v143
	v_and_b32_e32 v31, 0xffff0000, v143
	v_pk_mul_f32 v[30:31], v[22:23], v[30:31]
	v_pk_mul_f32 v[22:23], v[20:21], v[28:29]
	v_cvt_pk_bf16_f32 v20, v24, v25
	v_cvt_pk_bf16_f32 v21, v26, v27
	v_cvt_pk_bf16_f32 v22, v22, v23
	v_cvt_pk_bf16_f32 v23, v30, v31
	global_store_dwordx4 v[36:37], v[20:23], off offset:256
	s_nop 1
	v_lshl_add_u64 v[20:21], v[188:189], 0, v[2:3]
	v_lshlrev_b32_e32 v2, 16, v136
	v_and_b32_e32 v3, 0xffff0000, v136
	v_lshlrev_b32_e32 v22, 16, v137
	v_and_b32_e32 v23, 0xffff0000, v137
	v_pk_mul_f32 v[18:19], v[18:19], v[22:23]
	v_pk_mul_f32 v[2:3], v[16:17], v[2:3]
	v_lshlrev_b32_e32 v16, 16, v138
	v_and_b32_e32 v17, 0xffff0000, v138
	v_lshlrev_b32_e32 v22, 16, v139
	v_and_b32_e32 v23, 0xffff0000, v139
	v_pk_mul_f32 v[22:23], v[14:15], v[22:23]
	v_pk_mul_f32 v[14:15], v[12:13], v[16:17]
	v_cvt_pk_bf16_f32 v12, v2, v3
	v_cvt_pk_bf16_f32 v13, v18, v19
	v_cvt_pk_bf16_f32 v14, v14, v15
	v_cvt_pk_bf16_f32 v15, v22, v23
	global_store_dwordx4 v[20:21], v[12:15], off
	v_lshlrev_b32_e32 v2, 16, v132
	v_and_b32_e32 v3, 0xffff0000, v132
	v_lshlrev_b32_e32 v12, 16, v133
	v_and_b32_e32 v13, 0xffff0000, v133
	v_pk_mul_f32 v[10:11], v[10:11], v[12:13]
	v_pk_mul_f32 v[2:3], v[8:9], v[2:3]
	v_lshlrev_b32_e32 v8, 16, v134
	v_and_b32_e32 v9, 0xffff0000, v134
	v_lshlrev_b32_e32 v12, 16, v135
	v_and_b32_e32 v13, 0xffff0000, v135
	v_pk_mul_f32 v[6:7], v[6:7], v[12:13]
	v_pk_mul_f32 v[4:5], v[4:5], v[8:9]
	v_cvt_pk_bf16_f32 v2, v2, v3
	v_cvt_pk_bf16_f32 v3, v10, v11
	v_cvt_pk_bf16_f32 v4, v4, v5
	v_cvt_pk_bf16_f32 v5, v6, v7
	global_store_dwordx4 v[20:21], v[2:5], off offset:256
	s_cbranch_vccnz .LBB0_1298
	s_andn2_b64 vcc, exec, s[10:11]
	s_cbranch_vccnz .LBB0_1297
	s_barrier
	s_branch .LBB0_1297
